# adds: EpiNormRes ladder-1 xin loads software-pipelined 2 steps deep (2 xin register sets, counted vmcnt); empty last phase 14 left without its grid barrier
# speedup vs baseline: 1.0108x; 1.0092x over previous
;     __device__ __forceinline__ void operator()(f32x4 (&acc)[2][2][4][2], const Unit& u, int wr, int wc, int fr, int fq) const {
;     ...
; #pragma unroll
;         for (int ai = 0; ai < 2; ++ai)
; #pragma unroll
;             for (int m = 0; m < 4; ++m) { const int rl = ai * 128 + wr * 64 + m * 16 + fr; const float r1 = S[rl]; const size_t off = (size_t)(u.pm * 256 + rl) * DM + col0;
; #pragma unroll
;                 for (int bj = 0; bj < 2; ++bj) { const f32x4 xa = *(const f32x4*)(xin + off + bj * 128), xb = *(const f32x4*)(xin + off + bj * 128 + 4);
;                     const f32x4 ga = *(const f32x4*)(gpost + col0 + bj * 128), gb = *(const f32x4*)(gpost + col0 + bj * 128 + 4);
;                     const f32x4 v0 = xa + acc[ai][bj][m][0] * r1 * ga, v1 = xb + acc[ai][bj][m][1] * r1 * gb;
;                     *(f32x4*)(xout + off + bj * 128) = v0; *(f32x4*)(xout + off + bj * 128 + 4) = v1; acc[ai][bj][m][0] = v0; acc[ai][bj][m][1] = v1; }
;                 asm volatile("" ::: "memory"); }
.LBB0_103:
	s_or_b64 exec, exec, s[84:85]
	s_lshl_b32 s54, s82, 8
	v_add_u32_e32 v144, s54, v170
	v_lshl_or_b32 v142, s78, 8, v190
	v_ashrrev_i32_e32 v145, 31, v144
	v_ashrrev_i32_e32 v143, 31, v142
	v_lshlrev_b64 v[146:147], 12, v[144:145]
	v_lshl_add_u64 v[146:147], s[34:35], 0, v[146:147]
	v_lshlrev_b64 v[158:159], 2, v[142:143]
	v_lshl_add_u64 v[160:161], v[146:147], 0, v[158:159]
	v_lshl_add_u64 v[154:155], s[52:53], 0, v[158:159]
	global_load_dwordx4 v[218:221], v[154:155], off
	global_load_dwordx4 v[222:225], v[154:155], off offset:16
	global_load_dwordx4 v[226:229], v[154:155], off offset:512
	global_load_dwordx4 v[230:233], v[154:155], off offset:528
	s_waitcnt lgkmcnt(0)
	s_barrier
	s_andn2_b64 vcc, exec, s[62:63]
	ds_read_b32 v154, v182
	global_load_dwordx4 v[202:205], v[160:161], off offset:16
	global_load_dwordx4 v[206:209], v[160:161], off
	global_load_dwordx4 v[210:213], v[160:161], off offset:528
	global_load_dwordx4 v[214:217], v[160:161], off offset:512
	v_add_u32_e32 v164, s54, v173
	v_ashrrev_i32_e32 v165, 31, v164
	v_lshlrev_b64 v[164:165], 12, v[164:165]
	v_lshl_add_u64 v[164:165], s[34:35], 0, v[164:165]
	v_lshl_add_u64 v[162:163], v[164:165], 0, v[158:159]
	ds_read_b32 v156, v183
	global_load_dwordx4 v[234:237], v[162:163], off offset:16
	global_load_dwordx4 v[238:241], v[162:163], off
	global_load_dwordx4 v[146:149], v[162:163], off offset:528
	global_load_dwordx4 v[150:153], v[162:163], off offset:512
	s_waitcnt lgkmcnt(1)
	v_pk_mul_f32 v[50:51], v[50:51], v[154:155] op_sel_hi:[1,0]
	v_pk_mul_f32 v[52:53], v[52:53], v[154:155] op_sel_hi:[1,0]
	v_pk_mul_f32 v[54:55], v[54:55], v[154:155] op_sel_hi:[1,0]
	v_pk_mul_f32 v[56:57], v[56:57], v[154:155] op_sel_hi:[1,0]
	v_pk_mul_f32 v[62:63], v[62:63], v[154:155] op_sel_hi:[1,0]
	v_pk_mul_f32 v[64:65], v[64:65], v[154:155] op_sel_hi:[1,0]
	v_pk_mul_f32 v[58:59], v[58:59], v[154:155] op_sel_hi:[1,0]
	v_pk_mul_f32 v[60:61], v[60:61], v[154:155] op_sel_hi:[1,0]
	s_waitcnt vmcnt(4)
	v_pk_fma_f32 v[54:55], v[54:55], v[222:223], v[202:203]
	v_pk_fma_f32 v[56:57], v[56:57], v[224:225], v[204:205]
	v_pk_fma_f32 v[50:51], v[50:51], v[218:219], v[206:207]
	v_pk_fma_f32 v[52:53], v[52:53], v[220:221], v[208:209]
	v_pk_fma_f32 v[58:59], v[58:59], v[230:231], v[210:211]
	v_pk_fma_f32 v[60:61], v[60:61], v[232:233], v[212:213]
	v_pk_fma_f32 v[62:63], v[62:63], v[226:227], v[214:215]
	v_pk_fma_f32 v[64:65], v[64:65], v[228:229], v[216:217]
	global_store_dwordx4 v[160:161], v[50:53], off
	global_store_dwordx4 v[160:161], v[54:57], off offset:16
	global_store_dwordx4 v[160:161], v[62:65], off offset:512
	global_store_dwordx4 v[160:161], v[58:61], off offset:528
	v_add_u32_e32 v164, s54, v174
	v_ashrrev_i32_e32 v165, 31, v164
	v_lshlrev_b64 v[164:165], 12, v[164:165]
	v_lshl_add_u64 v[164:165], s[34:35], 0, v[164:165]
	v_lshl_add_u64 v[160:161], v[164:165], 0, v[158:159]
	ds_read_b32 v154, v184
	global_load_dwordx4 v[202:205], v[160:161], off offset:16
	global_load_dwordx4 v[206:209], v[160:161], off
	global_load_dwordx4 v[210:213], v[160:161], off offset:528
	global_load_dwordx4 v[214:217], v[160:161], off offset:512
	s_waitcnt lgkmcnt(1)
	v_pk_mul_f32 v[74:75], v[74:75], v[156:157] op_sel_hi:[1,0]
	v_pk_mul_f32 v[76:77], v[76:77], v[156:157] op_sel_hi:[1,0]
	v_pk_mul_f32 v[78:79], v[78:79], v[156:157] op_sel_hi:[1,0]
	v_pk_mul_f32 v[80:81], v[80:81], v[156:157] op_sel_hi:[1,0]
	v_pk_mul_f32 v[94:95], v[94:95], v[156:157] op_sel_hi:[1,0]
	v_pk_mul_f32 v[96:97], v[96:97], v[156:157] op_sel_hi:[1,0]
	v_pk_mul_f32 v[90:91], v[90:91], v[156:157] op_sel_hi:[1,0]
	v_pk_mul_f32 v[92:93], v[92:93], v[156:157] op_sel_hi:[1,0]
	s_waitcnt vmcnt(8)
	v_pk_fma_f32 v[78:79], v[78:79], v[222:223], v[234:235]
	v_pk_fma_f32 v[80:81], v[80:81], v[224:225], v[236:237]
	v_pk_fma_f32 v[74:75], v[74:75], v[218:219], v[238:239]
	v_pk_fma_f32 v[76:77], v[76:77], v[220:221], v[240:241]
	v_pk_fma_f32 v[90:91], v[90:91], v[230:231], v[146:147]
	v_pk_fma_f32 v[92:93], v[92:93], v[232:233], v[148:149]
	v_pk_fma_f32 v[94:95], v[94:95], v[226:227], v[150:151]
	v_pk_fma_f32 v[96:97], v[96:97], v[228:229], v[152:153]
	global_store_dwordx4 v[162:163], v[74:77], off
	global_store_dwordx4 v[162:163], v[78:81], off offset:16
	global_store_dwordx4 v[162:163], v[94:97], off offset:512
	global_store_dwordx4 v[162:163], v[90:93], off offset:528
	v_add_u32_e32 v164, s54, v175
	v_ashrrev_i32_e32 v165, 31, v164
	v_lshlrev_b64 v[164:165], 12, v[164:165]
	v_lshl_add_u64 v[164:165], s[34:35], 0, v[164:165]
	v_lshl_add_u64 v[162:163], v[164:165], 0, v[158:159]
	ds_read_b32 v156, v185
	global_load_dwordx4 v[234:237], v[162:163], off offset:16
	global_load_dwordx4 v[238:241], v[162:163], off
	global_load_dwordx4 v[146:149], v[162:163], off offset:528
	global_load_dwordx4 v[150:153], v[162:163], off offset:512
	s_waitcnt lgkmcnt(1)
	v_pk_mul_f32 v[98:99], v[98:99], v[154:155] op_sel_hi:[1,0]
	v_pk_mul_f32 v[100:101], v[100:101], v[154:155] op_sel_hi:[1,0]
	v_pk_mul_f32 v[102:103], v[102:103], v[154:155] op_sel_hi:[1,0]
	v_pk_mul_f32 v[104:105], v[104:105], v[154:155] op_sel_hi:[1,0]
	v_pk_mul_f32 v[118:119], v[118:119], v[154:155] op_sel_hi:[1,0]
	v_pk_mul_f32 v[120:121], v[120:121], v[154:155] op_sel_hi:[1,0]
	v_pk_mul_f32 v[114:115], v[114:115], v[154:155] op_sel_hi:[1,0]
	v_pk_mul_f32 v[116:117], v[116:117], v[154:155] op_sel_hi:[1,0]
	s_waitcnt vmcnt(8)
;     __device__ __forceinline__ void operator()(f32x4 (&acc)[2][2][4][2], const Unit& u, int wr, int wc, int fr, int fq) const {
;     ...
; #pragma unroll
;         for (int ai = 0; ai < 2; ++ai)
; #pragma unroll
;             for (int m = 0; m < 4; ++m) { const int rl = ai * 128 + wr * 64 + m * 16 + fr; const float r1 = S[rl]; const size_t off = (size_t)(u.pm * 256 + rl) * DM + col0;
; #pragma unroll
;                 for (int bj = 0; bj < 2; ++bj) { const f32x4 xa = *(const f32x4*)(xin + off + bj * 128), xb = *(const f32x4*)(xin + off + bj * 128 + 4);
;                     const f32x4 ga = *(const f32x4*)(gpost + col0 + bj * 128), gb = *(const f32x4*)(gpost + col0 + bj * 128 + 4);
;                     const f32x4 v0 = xa + acc[ai][bj][m][0] * r1 * ga, v1 = xb + acc[ai][bj][m][1] * r1 * gb;
;                     *(f32x4*)(xout + off + bj * 128) = v0; *(f32x4*)(xout + off + bj * 128 + 4) = v1; acc[ai][bj][m][0] = v0; acc[ai][bj][m][1] = v1; }
;                 asm volatile("" ::: "memory"); }
	v_pk_fma_f32 v[102:103], v[102:103], v[222:223], v[202:203]
	v_pk_fma_f32 v[104:105], v[104:105], v[224:225], v[204:205]
	v_pk_fma_f32 v[98:99], v[98:99], v[218:219], v[206:207]
	v_pk_fma_f32 v[100:101], v[100:101], v[220:221], v[208:209]
	v_pk_fma_f32 v[114:115], v[114:115], v[230:231], v[210:211]
	v_pk_fma_f32 v[116:117], v[116:117], v[232:233], v[212:213]
	v_pk_fma_f32 v[118:119], v[118:119], v[226:227], v[214:215]
	v_pk_fma_f32 v[120:121], v[120:121], v[228:229], v[216:217]
	global_store_dwordx4 v[160:161], v[98:101], off
	global_store_dwordx4 v[160:161], v[102:105], off offset:16
	global_store_dwordx4 v[160:161], v[118:121], off offset:512
	global_store_dwordx4 v[160:161], v[114:117], off offset:528
	v_add_u32_e32 v164, s54, v176
	v_ashrrev_i32_e32 v165, 31, v164
	v_lshlrev_b64 v[164:165], 12, v[164:165]
	v_lshl_add_u64 v[164:165], s[34:35], 0, v[164:165]
	v_lshl_add_u64 v[160:161], v[164:165], 0, v[158:159]
	ds_read_b32 v154, v186
	global_load_dwordx4 v[202:205], v[160:161], off offset:16
	global_load_dwordx4 v[206:209], v[160:161], off
	global_load_dwordx4 v[210:213], v[160:161], off offset:528
	global_load_dwordx4 v[214:217], v[160:161], off offset:512
	s_waitcnt lgkmcnt(1)
	v_pk_mul_f32 v[126:127], v[126:127], v[156:157] op_sel_hi:[1,0]
	v_pk_mul_f32 v[128:129], v[128:129], v[156:157] op_sel_hi:[1,0]
	v_pk_mul_f32 v[122:123], v[122:123], v[156:157] op_sel_hi:[1,0]
	v_pk_mul_f32 v[124:125], v[124:125], v[156:157] op_sel_hi:[1,0]
	v_pk_mul_f32 v[110:111], v[110:111], v[156:157] op_sel_hi:[1,0]
	v_pk_mul_f32 v[112:113], v[112:113], v[156:157] op_sel_hi:[1,0]
	v_pk_mul_f32 v[106:107], v[106:107], v[156:157] op_sel_hi:[1,0]
	v_pk_mul_f32 v[108:109], v[108:109], v[156:157] op_sel_hi:[1,0]
	s_waitcnt vmcnt(8)
	v_pk_fma_f32 v[122:123], v[122:123], v[222:223], v[234:235]
	v_pk_fma_f32 v[124:125], v[124:125], v[224:225], v[236:237]
	v_pk_fma_f32 v[126:127], v[126:127], v[218:219], v[238:239]
	v_pk_fma_f32 v[128:129], v[128:129], v[220:221], v[240:241]
	v_pk_fma_f32 v[106:107], v[106:107], v[230:231], v[146:147]
	v_pk_fma_f32 v[108:109], v[108:109], v[232:233], v[148:149]
	v_pk_fma_f32 v[110:111], v[110:111], v[226:227], v[150:151]
	v_pk_fma_f32 v[112:113], v[112:113], v[228:229], v[152:153]
	global_store_dwordx4 v[162:163], v[126:129], off
	global_store_dwordx4 v[162:163], v[122:125], off offset:16
	global_store_dwordx4 v[162:163], v[110:113], off offset:512
	global_store_dwordx4 v[162:163], v[106:109], off offset:528
	v_add_u32_e32 v164, s54, v177
	v_ashrrev_i32_e32 v165, 31, v164
	v_lshlrev_b64 v[164:165], 12, v[164:165]
	v_lshl_add_u64 v[164:165], s[34:35], 0, v[164:165]
	v_lshl_add_u64 v[162:163], v[164:165], 0, v[158:159]
	ds_read_b32 v156, v187
	global_load_dwordx4 v[234:237], v[162:163], off offset:16
	global_load_dwordx4 v[238:241], v[162:163], off
	global_load_dwordx4 v[146:149], v[162:163], off offset:528
	global_load_dwordx4 v[150:153], v[162:163], off offset:512
	s_waitcnt lgkmcnt(1)
	v_pk_mul_f32 v[86:87], v[86:87], v[154:155] op_sel_hi:[1,0]
	v_pk_mul_f32 v[88:89], v[88:89], v[154:155] op_sel_hi:[1,0]
	v_pk_mul_f32 v[82:83], v[82:83], v[154:155] op_sel_hi:[1,0]
	v_pk_mul_f32 v[84:85], v[84:85], v[154:155] op_sel_hi:[1,0]
	v_pk_mul_f32 v[70:71], v[70:71], v[154:155] op_sel_hi:[1,0]
	v_pk_mul_f32 v[72:73], v[72:73], v[154:155] op_sel_hi:[1,0]
	v_pk_mul_f32 v[66:67], v[66:67], v[154:155] op_sel_hi:[1,0]
	v_pk_mul_f32 v[68:69], v[68:69], v[154:155] op_sel_hi:[1,0]
	s_waitcnt vmcnt(8)
	v_pk_fma_f32 v[82:83], v[82:83], v[222:223], v[202:203]
	v_pk_fma_f32 v[84:85], v[84:85], v[224:225], v[204:205]
	v_pk_fma_f32 v[86:87], v[86:87], v[218:219], v[206:207]
	v_pk_fma_f32 v[88:89], v[88:89], v[220:221], v[208:209]
	v_pk_fma_f32 v[66:67], v[66:67], v[230:231], v[210:211]
	v_pk_fma_f32 v[68:69], v[68:69], v[232:233], v[212:213]
	v_pk_fma_f32 v[70:71], v[70:71], v[226:227], v[214:215]
	v_pk_fma_f32 v[72:73], v[72:73], v[228:229], v[216:217]
	global_store_dwordx4 v[160:161], v[86:89], off
	global_store_dwordx4 v[160:161], v[82:85], off offset:16
	global_store_dwordx4 v[160:161], v[70:73], off offset:512
	global_store_dwordx4 v[160:161], v[66:69], off offset:528
	v_add_u32_e32 v164, s54, v178
	v_ashrrev_i32_e32 v165, 31, v164
	v_lshlrev_b64 v[164:165], 12, v[164:165]
	v_lshl_add_u64 v[164:165], s[34:35], 0, v[164:165]
	v_lshl_add_u64 v[160:161], v[164:165], 0, v[158:159]
	ds_read_b32 v154, v188
	global_load_dwordx4 v[202:205], v[160:161], off offset:16
	global_load_dwordx4 v[206:209], v[160:161], off
	global_load_dwordx4 v[210:213], v[160:161], off offset:528
	global_load_dwordx4 v[214:217], v[160:161], off offset:512
	s_waitcnt lgkmcnt(1)
	v_pk_mul_f32 v[46:47], v[46:47], v[156:157] op_sel_hi:[1,0]
	v_pk_mul_f32 v[48:49], v[48:49], v[156:157] op_sel_hi:[1,0]
	v_pk_mul_f32 v[42:43], v[42:43], v[156:157] op_sel_hi:[1,0]
	v_pk_mul_f32 v[44:45], v[44:45], v[156:157] op_sel_hi:[1,0]
	v_pk_mul_f32 v[38:39], v[38:39], v[156:157] op_sel_hi:[1,0]
	v_pk_mul_f32 v[40:41], v[40:41], v[156:157] op_sel_hi:[1,0]
	v_pk_mul_f32 v[34:35], v[34:35], v[156:157] op_sel_hi:[1,0]
	v_pk_mul_f32 v[36:37], v[36:37], v[156:157] op_sel_hi:[1,0]
	s_waitcnt vmcnt(8)
; __device__ __forceinline__ float swap_add(float v) { auto rr = __builtin_amdgcn_permlane32_swap(__float_as_uint(v), __float_as_uint(v), false, false); return __uint_as_float(rr[0]) + __uint_as_float(rr[1]); }
;     __device__ __forceinline__ void exchange(const f32x4 (&acc)[2][2][4][2], const Unit& u, int e, int wr, int wc, int fr, int fq) const {
;     ...
;             for (int m = 0; m < 4; ++m) { float q = 0.f;
; #pragma unroll
;                 for (int bj = 0; bj < 2; ++bj)
; #pragma unroll
;                     for (int n = 0; n < 2; ++n) { const f32x4 v = acc[ai][bj][m][n]; q += (v[0] * v[0] + v[1] * v[1]) + (v[2] * v[2] + v[3] * v[3]); }
;                 q += __int_as_float(__builtin_amdgcn_ds_bpermute((lid ^ 16) << 2, __float_as_int(q))); q = swap_add(q);
;                 if (fq == 0) P[(ai * 128 + wr * 64 + m * 16 + fr) * 4 + wc] = q; }
;     __device__ __forceinline__ void operator()(f32x4 (&acc)[2][2][4][2], const Unit& u, int wr, int wc, int fr, int fq) const {
;     ...
; #pragma unroll
;         for (int ai = 0; ai < 2; ++ai)
; #pragma unroll
;             for (int m = 0; m < 4; ++m) { const int rl = ai * 128 + wr * 64 + m * 16 + fr; const float r1 = S[rl]; const size_t off = (size_t)(u.pm * 256 + rl) * DM + col0;
; #pragma unroll
;                 for (int bj = 0; bj < 2; ++bj) { const f32x4 xa = *(const f32x4*)(xin + off + bj * 128), xb = *(const f32x4*)(xin + off + bj * 128 + 4);
;                     const f32x4 ga = *(const f32x4*)(gpost + col0 + bj * 128), gb = *(const f32x4*)(gpost + col0 + bj * 128 + 4);
;                     const f32x4 v0 = xa + acc[ai][bj][m][0] * r1 * ga, v1 = xb + acc[ai][bj][m][1] * r1 * gb;
;                     *(f32x4*)(xout + off + bj * 128) = v0; *(f32x4*)(xout + off + bj * 128 + 4) = v1; acc[ai][bj][m][0] = v0; acc[ai][bj][m][1] = v1; }
;                 asm volatile("" ::: "memory"); }
	v_pk_fma_f32 v[42:43], v[42:43], v[222:223], v[234:235]
	v_pk_fma_f32 v[44:45], v[44:45], v[224:225], v[236:237]
	v_pk_fma_f32 v[46:47], v[46:47], v[218:219], v[238:239]
	v_pk_fma_f32 v[48:49], v[48:49], v[220:221], v[240:241]
	v_pk_fma_f32 v[34:35], v[34:35], v[230:231], v[146:147]
	v_pk_fma_f32 v[36:37], v[36:37], v[232:233], v[148:149]
	v_pk_fma_f32 v[38:39], v[38:39], v[226:227], v[150:151]
	v_pk_fma_f32 v[40:41], v[40:41], v[228:229], v[152:153]
	global_store_dwordx4 v[162:163], v[46:49], off
	global_store_dwordx4 v[162:163], v[42:45], off offset:16
	global_store_dwordx4 v[162:163], v[38:41], off offset:512
	global_store_dwordx4 v[162:163], v[34:37], off offset:528
	v_add_u32_e32 v164, s54, v179
	v_ashrrev_i32_e32 v165, 31, v164
	v_lshlrev_b64 v[164:165], 12, v[164:165]
	v_lshl_add_u64 v[164:165], s[34:35], 0, v[164:165]
	v_lshl_add_u64 v[162:163], v[164:165], 0, v[158:159]
	ds_read_b32 v156, v189
	global_load_dwordx4 v[234:237], v[162:163], off offset:16
	global_load_dwordx4 v[238:241], v[162:163], off
	global_load_dwordx4 v[146:149], v[162:163], off offset:528
	global_load_dwordx4 v[150:153], v[162:163], off offset:512
	s_waitcnt lgkmcnt(1)
	v_pk_mul_f32 v[30:31], v[30:31], v[154:155] op_sel_hi:[1,0]
	v_pk_mul_f32 v[32:33], v[32:33], v[154:155] op_sel_hi:[1,0]
	v_pk_mul_f32 v[26:27], v[26:27], v[154:155] op_sel_hi:[1,0]
	v_pk_mul_f32 v[28:29], v[28:29], v[154:155] op_sel_hi:[1,0]
	v_pk_mul_f32 v[22:23], v[22:23], v[154:155] op_sel_hi:[1,0]
	v_pk_mul_f32 v[24:25], v[24:25], v[154:155] op_sel_hi:[1,0]
	v_pk_mul_f32 v[18:19], v[18:19], v[154:155] op_sel_hi:[1,0]
	v_pk_mul_f32 v[20:21], v[20:21], v[154:155] op_sel_hi:[1,0]
	s_waitcnt vmcnt(8)
	v_pk_fma_f32 v[26:27], v[26:27], v[222:223], v[202:203]
	v_pk_fma_f32 v[28:29], v[28:29], v[224:225], v[204:205]
	v_pk_fma_f32 v[30:31], v[30:31], v[218:219], v[206:207]
	v_pk_fma_f32 v[32:33], v[32:33], v[220:221], v[208:209]
	v_pk_fma_f32 v[18:19], v[18:19], v[230:231], v[210:211]
	v_pk_fma_f32 v[20:21], v[20:21], v[232:233], v[212:213]
	v_pk_fma_f32 v[22:23], v[22:23], v[226:227], v[214:215]
	v_pk_fma_f32 v[24:25], v[24:25], v[228:229], v[216:217]
	global_store_dwordx4 v[160:161], v[30:33], off
	global_store_dwordx4 v[160:161], v[26:29], off offset:16
	global_store_dwordx4 v[160:161], v[22:25], off offset:512
	global_store_dwordx4 v[160:161], v[18:21], off offset:528
	s_waitcnt lgkmcnt(0)
	v_pk_mul_f32 v[14:15], v[14:15], v[156:157] op_sel_hi:[1,0]
	v_pk_mul_f32 v[16:17], v[16:17], v[156:157] op_sel_hi:[1,0]
	v_pk_mul_f32 v[10:11], v[10:11], v[156:157] op_sel_hi:[1,0]
	v_pk_mul_f32 v[12:13], v[12:13], v[156:157] op_sel_hi:[1,0]
	v_pk_mul_f32 v[6:7], v[6:7], v[156:157] op_sel_hi:[1,0]
	v_pk_mul_f32 v[8:9], v[8:9], v[156:157] op_sel_hi:[1,0]
	v_pk_mul_f32 v[2:3], v[2:3], v[156:157] op_sel_hi:[1,0]
	v_pk_mul_f32 v[4:5], v[4:5], v[156:157] op_sel_hi:[1,0]
	s_waitcnt vmcnt(4)
	v_pk_fma_f32 v[10:11], v[10:11], v[222:223], v[234:235]
	v_pk_fma_f32 v[12:13], v[12:13], v[224:225], v[236:237]
	v_pk_fma_f32 v[14:15], v[14:15], v[218:219], v[238:239]
	v_pk_fma_f32 v[16:17], v[16:17], v[220:221], v[240:241]
	v_pk_fma_f32 v[2:3], v[2:3], v[230:231], v[146:147]
	v_pk_fma_f32 v[4:5], v[4:5], v[232:233], v[148:149]
	v_pk_fma_f32 v[6:7], v[6:7], v[226:227], v[150:151]
	v_pk_fma_f32 v[8:9], v[8:9], v[228:229], v[152:153]
	global_store_dwordx4 v[162:163], v[14:17], off
	global_store_dwordx4 v[162:163], v[10:13], off offset:16
	global_store_dwordx4 v[162:163], v[6:9], off offset:512
	global_store_dwordx4 v[162:163], v[2:5], off offset:528
	v_add_u32_e32 v146, s54, v173
	v_ashrrev_i32_e32 v147, 31, v146
	v_add_u32_e32 v148, s54, v174
	v_ashrrev_i32_e32 v149, 31, v148
	v_add_u32_e32 v150, s54, v175
	v_ashrrev_i32_e32 v151, 31, v150
	v_add_u32_e32 v152, s54, v176
	v_ashrrev_i32_e32 v153, 31, v152
	v_add_u32_e32 v156, s54, v177
	v_ashrrev_i32_e32 v157, 31, v156
	v_add_u32_e32 v166, s54, v178
	v_ashrrev_i32_e32 v167, 31, v166
	v_add_u32_e32 v168, s54, v179
	v_ashrrev_i32_e32 v169, 31, v168
	s_cbranch_vccnz .LBB0_140
	v_mul_f32_e32 v154, v51, v51
	v_mul_f32_e32 v155, v53, v53
	v_fmac_f32_e32 v154, v50, v50
	v_fmac_f32_e32 v155, v52, v52
	v_add_f32_e32 v154, v154, v155
	v_mul_f32_e32 v155, v55, v55
	v_mul_f32_e32 v158, v57, v57
	v_fmac_f32_e32 v155, v54, v54
	v_fmac_f32_e32 v158, v56, v56
	v_add_f32_e32 v155, v155, v158
	v_add_f32_e32 v154, v154, v155
	v_mul_f32_e32 v155, v63, v63
	v_mul_f32_e32 v158, v65, v65
	v_fmac_f32_e32 v155, v62, v62
	v_fmac_f32_e32 v158, v64, v64
	v_add_f32_e32 v155, v155, v158
	v_add_f32_e32 v154, v154, v155
	v_mul_f32_e32 v155, v59, v59
	v_mul_f32_e32 v158, v61, v61
	v_fmac_f32_e32 v155, v58, v58
	v_fmac_f32_e32 v158, v60, v60
	v_add_f32_e32 v155, v155, v158
	v_add_f32_e32 v154, v154, v155
	ds_bpermute_b32 v155, v172, v154
	s_waitcnt lgkmcnt(0)
	v_add_f32_e32 v154, v154, v155
	v_mov_b32_e32 v155, v154
	s_nop 1
	v_permlane32_swap_b32_e32 v154, v155
	s_and_saveexec_b64 s[54:55], s[42:43]
	v_add_f32_e32 v154, v154, v155
	ds_write_b32 v201, v154
	s_or_b64 exec, exec, s[54:55]
	v_mul_f32_e32 v154, v75, v75
	v_mul_f32_e32 v155, v77, v77
	v_fmac_f32_e32 v154, v74, v74
	v_fmac_f32_e32 v155, v76, v76
	v_add_f32_e32 v154, v154, v155
	v_mul_f32_e32 v155, v79, v79
	v_mul_f32_e32 v158, v81, v81
	v_fmac_f32_e32 v155, v78, v78
	v_fmac_f32_e32 v158, v80, v80
	v_add_f32_e32 v155, v155, v158
	v_add_f32_e32 v154, v154, v155
	v_mul_f32_e32 v155, v95, v95
	v_mul_f32_e32 v158, v97, v97
	v_fmac_f32_e32 v155, v94, v94
	v_fmac_f32_e32 v158, v96, v96
	v_add_f32_e32 v155, v155, v158
	v_add_f32_e32 v154, v154, v155
	v_mul_f32_e32 v155, v91, v91
	v_mul_f32_e32 v158, v93, v93
	v_fmac_f32_e32 v155, v90, v90
	v_fmac_f32_e32 v158, v92, v92
	v_add_f32_e32 v155, v155, v158
	v_add_f32_e32 v154, v154, v155
	ds_bpermute_b32 v155, v172, v154
	s_waitcnt lgkmcnt(0)
; __device__ __forceinline__ float swap_add(float v) { auto rr = __builtin_amdgcn_permlane32_swap(__float_as_uint(v), __float_as_uint(v), false, false); return __uint_as_float(rr[0]) + __uint_as_float(rr[1]); }
;     __device__ __forceinline__ void exchange(const f32x4 (&acc)[2][2][4][2], const Unit& u, int e, int wr, int wc, int fr, int fq) const {
;     ...
;             for (int m = 0; m < 4; ++m) { float q = 0.f;
; #pragma unroll
;                 for (int bj = 0; bj < 2; ++bj)
; #pragma unroll
;                     for (int n = 0; n < 2; ++n) { const f32x4 v = acc[ai][bj][m][n]; q += (v[0] * v[0] + v[1] * v[1]) + (v[2] * v[2] + v[3] * v[3]); }
;                 q += __int_as_float(__builtin_amdgcn_ds_bpermute((lid ^ 16) << 2, __float_as_int(q))); q = swap_add(q);
;                 if (fq == 0) P[(ai * 128 + wr * 64 + m * 16 + fr) * 4 + wc] = q; }
;         __syncthreads();
;         float* xb = xbuf + (size_t)e * T * 4 + (size_t)u.pm * 256 * 4; unsigned* c = cnt + (e * 64 + u.pm) * 64;
;         if (tid < 256) { const float tot = (P[tid * 4] + P[tid * 4 + 1]) + (P[tid * 4 + 2] + P[tid * 4 + 3]);
;             __hip_atomic_store(xb + tid * 4 + u.pn, tot, __ATOMIC_RELAXED, __HIP_MEMORY_SCOPE_AGENT); }
	v_add_f32_e32 v154, v154, v155
	v_mov_b32_e32 v155, v154
	s_nop 1
	v_permlane32_swap_b32_e32 v154, v155
	s_and_saveexec_b64 s[54:55], s[42:43]
	v_add_f32_e32 v154, v154, v155
	ds_write_b32 v201, v154 offset:256
	s_or_b64 exec, exec, s[54:55]
	v_mul_f32_e32 v154, v99, v99
	v_mul_f32_e32 v155, v101, v101
	v_fmac_f32_e32 v154, v98, v98
	v_fmac_f32_e32 v155, v100, v100
	v_add_f32_e32 v154, v154, v155
	v_mul_f32_e32 v155, v103, v103
	v_mul_f32_e32 v158, v105, v105
	v_fmac_f32_e32 v155, v102, v102
	v_fmac_f32_e32 v158, v104, v104
	v_add_f32_e32 v155, v155, v158
	v_add_f32_e32 v154, v154, v155
	v_mul_f32_e32 v155, v119, v119
	v_mul_f32_e32 v158, v121, v121
	v_fmac_f32_e32 v155, v118, v118
	v_fmac_f32_e32 v158, v120, v120
	v_add_f32_e32 v155, v155, v158
	v_add_f32_e32 v154, v154, v155
	v_mul_f32_e32 v155, v115, v115
	v_mul_f32_e32 v158, v117, v117
	v_fmac_f32_e32 v155, v114, v114
	v_fmac_f32_e32 v158, v116, v116
	v_add_f32_e32 v155, v155, v158
	v_add_f32_e32 v154, v154, v155
	ds_bpermute_b32 v155, v172, v154
	s_waitcnt lgkmcnt(0)
	v_add_f32_e32 v154, v154, v155
	v_mov_b32_e32 v155, v154
	s_nop 1
	v_permlane32_swap_b32_e32 v154, v155
	s_and_saveexec_b64 s[54:55], s[42:43]
	v_add_f32_e32 v154, v154, v155
	ds_write_b32 v201, v154 offset:512
	s_or_b64 exec, exec, s[54:55]
	v_mul_f32_e32 v154, v127, v127
	v_mul_f32_e32 v155, v129, v129
	v_fmac_f32_e32 v154, v126, v126
	v_fmac_f32_e32 v155, v128, v128
	v_add_f32_e32 v154, v154, v155
	v_mul_f32_e32 v155, v123, v123
	v_mul_f32_e32 v158, v125, v125
	v_fmac_f32_e32 v155, v122, v122
	v_fmac_f32_e32 v158, v124, v124
	v_add_f32_e32 v155, v155, v158
	v_add_f32_e32 v154, v154, v155
	v_mul_f32_e32 v155, v111, v111
	v_mul_f32_e32 v158, v113, v113
	v_fmac_f32_e32 v155, v110, v110
	v_fmac_f32_e32 v158, v112, v112
	v_add_f32_e32 v155, v155, v158
	v_add_f32_e32 v154, v154, v155
	v_mul_f32_e32 v155, v107, v107
	v_mul_f32_e32 v158, v109, v109
	v_fmac_f32_e32 v155, v106, v106
	v_fmac_f32_e32 v158, v108, v108
	v_add_f32_e32 v155, v155, v158
	v_add_f32_e32 v154, v154, v155
	ds_bpermute_b32 v155, v172, v154
	s_waitcnt lgkmcnt(0)
	v_add_f32_e32 v154, v154, v155
	v_mov_b32_e32 v155, v154
	s_nop 1
	v_permlane32_swap_b32_e32 v154, v155
	s_and_saveexec_b64 s[54:55], s[42:43]
	v_add_f32_e32 v154, v154, v155
	ds_write_b32 v201, v154 offset:768
	s_or_b64 exec, exec, s[54:55]
	v_mul_f32_e32 v154, v87, v87
	v_mul_f32_e32 v155, v89, v89
	v_fmac_f32_e32 v154, v86, v86
	v_fmac_f32_e32 v155, v88, v88
	v_add_f32_e32 v154, v154, v155
	v_mul_f32_e32 v155, v83, v83
	v_mul_f32_e32 v158, v85, v85
	v_fmac_f32_e32 v155, v82, v82
	v_fmac_f32_e32 v158, v84, v84
	v_add_f32_e32 v155, v155, v158
	v_add_f32_e32 v154, v154, v155
	v_mul_f32_e32 v155, v71, v71
	v_mul_f32_e32 v158, v73, v73
	v_fmac_f32_e32 v155, v70, v70
	v_fmac_f32_e32 v158, v72, v72
	v_add_f32_e32 v155, v155, v158
	v_add_f32_e32 v154, v154, v155
	v_mul_f32_e32 v155, v67, v67
	v_mul_f32_e32 v158, v69, v69
	v_fmac_f32_e32 v155, v66, v66
	v_fmac_f32_e32 v158, v68, v68
	v_add_f32_e32 v155, v155, v158
	v_add_f32_e32 v154, v154, v155
	ds_bpermute_b32 v155, v172, v154
	s_waitcnt lgkmcnt(0)
	v_add_f32_e32 v154, v154, v155
	v_mov_b32_e32 v155, v154
	s_nop 1
	v_permlane32_swap_b32_e32 v154, v155
	s_and_saveexec_b64 s[54:55], s[42:43]
	v_add_f32_e32 v154, v154, v155
	ds_write_b32 v201, v154 offset:2048
	s_or_b64 exec, exec, s[54:55]
	v_mul_f32_e32 v154, v47, v47
	v_mul_f32_e32 v155, v49, v49
	v_fmac_f32_e32 v154, v46, v46
	v_fmac_f32_e32 v155, v48, v48
	v_add_f32_e32 v154, v154, v155
	v_mul_f32_e32 v155, v43, v43
	v_mul_f32_e32 v158, v45, v45
	v_fmac_f32_e32 v155, v42, v42
	v_fmac_f32_e32 v158, v44, v44
	v_add_f32_e32 v155, v155, v158
	v_add_f32_e32 v154, v154, v155
	v_mul_f32_e32 v155, v39, v39
	v_mul_f32_e32 v158, v41, v41
	v_fmac_f32_e32 v155, v38, v38
	v_fmac_f32_e32 v158, v40, v40
	v_add_f32_e32 v155, v155, v158
	v_add_f32_e32 v154, v154, v155
	v_mul_f32_e32 v155, v35, v35
	v_mul_f32_e32 v158, v37, v37
	v_fmac_f32_e32 v155, v34, v34
	v_fmac_f32_e32 v158, v36, v36
	v_add_f32_e32 v155, v155, v158
	v_add_f32_e32 v154, v154, v155
	ds_bpermute_b32 v155, v172, v154
	s_waitcnt lgkmcnt(0)
	v_add_f32_e32 v154, v154, v155
	v_mov_b32_e32 v155, v154
	s_nop 1
	v_permlane32_swap_b32_e32 v154, v155
	s_and_saveexec_b64 s[54:55], s[42:43]
	v_add_f32_e32 v154, v154, v155
	ds_write_b32 v201, v154 offset:2304
	s_or_b64 exec, exec, s[54:55]
	v_mul_f32_e32 v154, v31, v31
	v_mul_f32_e32 v155, v33, v33
	v_fmac_f32_e32 v154, v30, v30
	v_fmac_f32_e32 v155, v32, v32
	v_add_f32_e32 v154, v154, v155
	v_mul_f32_e32 v155, v27, v27
	v_mul_f32_e32 v158, v29, v29
	v_fmac_f32_e32 v155, v26, v26
	v_fmac_f32_e32 v158, v28, v28
	v_add_f32_e32 v155, v155, v158
	v_add_f32_e32 v154, v154, v155
	v_mul_f32_e32 v155, v23, v23
	v_mul_f32_e32 v158, v25, v25
	v_fmac_f32_e32 v155, v22, v22
	v_fmac_f32_e32 v158, v24, v24
	v_add_f32_e32 v155, v155, v158
	v_add_f32_e32 v154, v154, v155
	v_mul_f32_e32 v155, v19, v19
	v_mul_f32_e32 v158, v21, v21
	v_fmac_f32_e32 v155, v18, v18
	v_fmac_f32_e32 v158, v20, v20
	v_add_f32_e32 v155, v155, v158
	v_add_f32_e32 v154, v154, v155
	ds_bpermute_b32 v155, v172, v154
	s_waitcnt lgkmcnt(0)
	v_add_f32_e32 v154, v154, v155
	v_mov_b32_e32 v155, v154
	s_nop 1
	v_permlane32_swap_b32_e32 v154, v155
	s_and_saveexec_b64 s[54:55], s[42:43]
	v_add_f32_e32 v154, v154, v155
	ds_write_b32 v201, v154 offset:2560
	s_or_b64 exec, exec, s[54:55]
	v_mul_f32_e32 v154, v15, v15
	v_mul_f32_e32 v155, v17, v17
	v_fmac_f32_e32 v154, v14, v14
	v_fmac_f32_e32 v155, v16, v16
	v_add_f32_e32 v154, v154, v155
	v_mul_f32_e32 v155, v11, v11
	v_mul_f32_e32 v158, v13, v13
	v_fmac_f32_e32 v155, v10, v10
	v_fmac_f32_e32 v158, v12, v12
	v_add_f32_e32 v155, v155, v158
	v_add_f32_e32 v154, v154, v155
	v_mul_f32_e32 v155, v7, v7
	v_mul_f32_e32 v158, v9, v9
	v_fmac_f32_e32 v155, v6, v6
	v_fmac_f32_e32 v158, v8, v8
	v_add_f32_e32 v155, v155, v158
	v_add_f32_e32 v154, v154, v155
	v_mul_f32_e32 v155, v3, v3
	v_mul_f32_e32 v158, v5, v5
	v_fmac_f32_e32 v155, v2, v2
	v_fmac_f32_e32 v158, v4, v4
	v_add_f32_e32 v155, v155, v158
	v_add_f32_e32 v154, v154, v155
	ds_bpermute_b32 v155, v172, v154
	s_waitcnt lgkmcnt(0)
	v_add_f32_e32 v154, v154, v155
	v_mov_b32_e32 v155, v154
	s_nop 1
	v_permlane32_swap_b32_e32 v154, v155
	s_and_saveexec_b64 s[54:55], s[42:43]
	v_add_f32_e32 v154, v154, v155
	ds_write_b32 v201, v154 offset:2816
	s_or_b64 exec, exec, s[54:55]
	s_add_u32 s12, s92, s12
	s_addc_u32 s13, s94, s13
	v_lshl_add_u64 v[154:155], v[136:137], 2, s[12:13]
	s_waitcnt lgkmcnt(0)
	s_barrier
	s_and_saveexec_b64 s[12:13], s[44:45]
	s_cbranch_execz .LBB0_122
	ds_read_b128 v[202:205], v180
	s_ashr_i32 s79, s78, 31
	v_lshl_add_u64 v[160:161], s[78:79], 2, v[154:155]
	s_waitcnt lgkmcnt(0)
	v_mov_b32_e32 v158, v203
	v_mov_b32_e32 v159, v204
	v_mov_b32_e32 v203, v205
	v_pk_add_f32 v[158:159], v[158:159], v[202:203]
	s_nop 0
	v_pk_add_f32 v[158:159], v[158:159], v[158:159] op_sel:[0,1] op_sel_hi:[1,0]
	global_store_dword v[160:161], v158, off sc1

;     __device__ __forceinline__ void operator()(f32x4 (&acc)[2][2][4][2], const Unit& u, int wr, int wc, int fr, int fq) const {
;     ...
; #pragma unroll
;         for (int ai = 0; ai < 2; ++ai)
; #pragma unroll
;             for (int m = 0; m < 4; ++m) { const int rl = ai * 128 + wr * 64 + m * 16 + fr; const float r1 = S[rl]; const size_t off = (size_t)(u.pm * 256 + rl) * DM + col0;
; #pragma unroll
;                 for (int bj = 0; bj < 2; ++bj) { const f32x4 xa = *(const f32x4*)(xin + off + bj * 128), xb = *(const f32x4*)(xin + off + bj * 128 + 4);
;                     const f32x4 ga = *(const f32x4*)(gpost + col0 + bj * 128), gb = *(const f32x4*)(gpost + col0 + bj * 128 + 4);
;                     const f32x4 v0 = xa + acc[ai][bj][m][0] * r1 * ga, v1 = xb + acc[ai][bj][m][1] * r1 * gb;
;                     *(f32x4*)(xout + off + bj * 128) = v0; *(f32x4*)(xout + off + bj * 128 + 4) = v1; acc[ai][bj][m][0] = v0; acc[ai][bj][m][1] = v1; }
;                 asm volatile("" ::: "memory"); }
.LBB0_235:
	s_or_b64 exec, exec, s[84:85]
	s_lshl_b32 s54, s82, 8
	v_add_u32_e32 v144, s54, v169
	v_lshl_or_b32 v142, s76, 8, v189
	v_ashrrev_i32_e32 v145, 31, v144
	v_ashrrev_i32_e32 v143, 31, v142
	v_lshlrev_b64 v[146:147], 10, v[144:145]
	v_lshl_add_u64 v[146:147], v[146:147], 0, v[142:143]
	v_lshlrev_b64 v[162:163], 2, v[146:147]
	v_lshl_add_u64 v[164:165], s[34:35], 0, v[162:163]
	v_lshl_add_u64 v[154:155], v[142:143], 2, s[52:53]
	global_load_dwordx4 v[218:221], v[154:155], off
	global_load_dwordx4 v[222:225], v[154:155], off offset:16
	global_load_dwordx4 v[226:229], v[154:155], off offset:512
	global_load_dwordx4 v[230:233], v[154:155], off offset:528
	s_waitcnt lgkmcnt(0)
	s_barrier
	s_andn2_b64 vcc, exec, s[70:71]
	ds_read_b32 v154, v181
	global_load_dwordx4 v[202:205], v[164:165], off offset:16
	global_load_dwordx4 v[206:209], v[164:165], off
	global_load_dwordx4 v[210:213], v[164:165], off offset:528
	global_load_dwordx4 v[214:217], v[164:165], off offset:512
	v_lshl_add_u64 v[162:163], s[14:15], 0, v[162:163]
	v_add_u32_e32 v250, s54, v172
	v_ashrrev_i32_e32 v251, 31, v250
	v_lshlrev_b64 v[250:251], 10, v[250:251]
	v_lshl_add_u64 v[250:251], v[250:251], 0, v[142:143]
	v_lshlrev_b64 v[250:251], 2, v[250:251]
	v_lshl_add_u64 v[158:159], s[34:35], 0, v[250:251]
	v_lshl_add_u64 v[160:161], s[14:15], 0, v[250:251]
	ds_read_b32 v156, v182
	global_load_dwordx4 v[234:237], v[158:159], off offset:16
	global_load_dwordx4 v[238:241], v[158:159], off
	global_load_dwordx4 v[146:149], v[158:159], off offset:528
	global_load_dwordx4 v[150:153], v[158:159], off offset:512
	s_waitcnt lgkmcnt(1)
	v_pk_mul_f32 v[42:43], v[42:43], v[154:155] op_sel_hi:[1,0]
	v_pk_mul_f32 v[44:45], v[44:45], v[154:155] op_sel_hi:[1,0]
	v_pk_mul_f32 v[46:47], v[46:47], v[154:155] op_sel_hi:[1,0]
	v_pk_mul_f32 v[48:49], v[48:49], v[154:155] op_sel_hi:[1,0]
	v_pk_mul_f32 v[62:63], v[62:63], v[154:155] op_sel_hi:[1,0]
	v_pk_mul_f32 v[64:65], v[64:65], v[154:155] op_sel_hi:[1,0]
	v_pk_mul_f32 v[58:59], v[58:59], v[154:155] op_sel_hi:[1,0]
	v_pk_mul_f32 v[60:61], v[60:61], v[154:155] op_sel_hi:[1,0]
	s_waitcnt vmcnt(4)
	v_pk_fma_f32 v[46:47], v[46:47], v[222:223], v[202:203]
	v_pk_fma_f32 v[48:49], v[48:49], v[224:225], v[204:205]
	v_pk_fma_f32 v[42:43], v[42:43], v[218:219], v[206:207]
	v_pk_fma_f32 v[44:45], v[44:45], v[220:221], v[208:209]
	v_pk_fma_f32 v[58:59], v[58:59], v[230:231], v[210:211]
	v_pk_fma_f32 v[60:61], v[60:61], v[232:233], v[212:213]
	v_pk_fma_f32 v[62:63], v[62:63], v[226:227], v[214:215]
	v_pk_fma_f32 v[64:65], v[64:65], v[228:229], v[216:217]
	global_store_dwordx4 v[162:163], v[42:45], off
	global_store_dwordx4 v[162:163], v[46:49], off offset:16
	global_store_dwordx4 v[162:163], v[62:65], off offset:512
	global_store_dwordx4 v[162:163], v[58:61], off offset:528
	v_add_u32_e32 v250, s54, v173
	v_ashrrev_i32_e32 v251, 31, v250
	v_lshlrev_b64 v[250:251], 10, v[250:251]
	v_lshl_add_u64 v[250:251], v[250:251], 0, v[142:143]
	v_lshlrev_b64 v[250:251], 2, v[250:251]
	v_lshl_add_u64 v[164:165], s[34:35], 0, v[250:251]
	v_lshl_add_u64 v[162:163], s[14:15], 0, v[250:251]
	ds_read_b32 v154, v183
	global_load_dwordx4 v[202:205], v[164:165], off offset:16
	global_load_dwordx4 v[206:209], v[164:165], off
	global_load_dwordx4 v[210:213], v[164:165], off offset:528
	global_load_dwordx4 v[214:217], v[164:165], off offset:512
	s_waitcnt lgkmcnt(1)
	v_pk_mul_f32 v[66:67], v[66:67], v[156:157] op_sel_hi:[1,0]
	v_pk_mul_f32 v[68:69], v[68:69], v[156:157] op_sel_hi:[1,0]
	v_pk_mul_f32 v[70:71], v[70:71], v[156:157] op_sel_hi:[1,0]
	v_pk_mul_f32 v[72:73], v[72:73], v[156:157] op_sel_hi:[1,0]
	v_pk_mul_f32 v[86:87], v[86:87], v[156:157] op_sel_hi:[1,0]
	v_pk_mul_f32 v[88:89], v[88:89], v[156:157] op_sel_hi:[1,0]
	v_pk_mul_f32 v[82:83], v[82:83], v[156:157] op_sel_hi:[1,0]
	v_pk_mul_f32 v[84:85], v[84:85], v[156:157] op_sel_hi:[1,0]
	s_waitcnt vmcnt(8)
	v_pk_fma_f32 v[70:71], v[70:71], v[222:223], v[234:235]
	v_pk_fma_f32 v[72:73], v[72:73], v[224:225], v[236:237]
	v_pk_fma_f32 v[66:67], v[66:67], v[218:219], v[238:239]
	v_pk_fma_f32 v[68:69], v[68:69], v[220:221], v[240:241]
	v_pk_fma_f32 v[82:83], v[82:83], v[230:231], v[146:147]
	v_pk_fma_f32 v[84:85], v[84:85], v[232:233], v[148:149]
	v_pk_fma_f32 v[86:87], v[86:87], v[226:227], v[150:151]
	v_pk_fma_f32 v[88:89], v[88:89], v[228:229], v[152:153]
	global_store_dwordx4 v[160:161], v[66:69], off
	global_store_dwordx4 v[160:161], v[70:73], off offset:16
	global_store_dwordx4 v[160:161], v[86:89], off offset:512
	global_store_dwordx4 v[160:161], v[82:85], off offset:528
	v_add_u32_e32 v250, s54, v174
	v_ashrrev_i32_e32 v251, 31, v250
	v_lshlrev_b64 v[250:251], 10, v[250:251]
	v_lshl_add_u64 v[250:251], v[250:251], 0, v[142:143]
	v_lshlrev_b64 v[250:251], 2, v[250:251]
	v_lshl_add_u64 v[158:159], s[34:35], 0, v[250:251]
	v_lshl_add_u64 v[160:161], s[14:15], 0, v[250:251]
	ds_read_b32 v156, v184
	global_load_dwordx4 v[234:237], v[158:159], off offset:16
	global_load_dwordx4 v[238:241], v[158:159], off
	global_load_dwordx4 v[146:149], v[158:159], off offset:528
	global_load_dwordx4 v[150:153], v[158:159], off offset:512
	s_waitcnt lgkmcnt(1)
	v_pk_mul_f32 v[98:99], v[98:99], v[154:155] op_sel_hi:[1,0]
	v_pk_mul_f32 v[100:101], v[100:101], v[154:155] op_sel_hi:[1,0]
	v_pk_mul_f32 v[102:103], v[102:103], v[154:155] op_sel_hi:[1,0]
	v_pk_mul_f32 v[104:105], v[104:105], v[154:155] op_sel_hi:[1,0]
	v_pk_mul_f32 v[110:111], v[110:111], v[154:155] op_sel_hi:[1,0]
	v_pk_mul_f32 v[112:113], v[112:113], v[154:155] op_sel_hi:[1,0]
	v_pk_mul_f32 v[106:107], v[106:107], v[154:155] op_sel_hi:[1,0]
	v_pk_mul_f32 v[108:109], v[108:109], v[154:155] op_sel_hi:[1,0]
	s_waitcnt vmcnt(8)
;     __device__ __forceinline__ void operator()(f32x4 (&acc)[2][2][4][2], const Unit& u, int wr, int wc, int fr, int fq) const {
;     ...
; #pragma unroll
;         for (int ai = 0; ai < 2; ++ai)
; #pragma unroll
;             for (int m = 0; m < 4; ++m) { const int rl = ai * 128 + wr * 64 + m * 16 + fr; const float r1 = S[rl]; const size_t off = (size_t)(u.pm * 256 + rl) * DM + col0;
; #pragma unroll
;                 for (int bj = 0; bj < 2; ++bj) { const f32x4 xa = *(const f32x4*)(xin + off + bj * 128), xb = *(const f32x4*)(xin + off + bj * 128 + 4);
;                     const f32x4 ga = *(const f32x4*)(gpost + col0 + bj * 128), gb = *(const f32x4*)(gpost + col0 + bj * 128 + 4);
;                     const f32x4 v0 = xa + acc[ai][bj][m][0] * r1 * ga, v1 = xb + acc[ai][bj][m][1] * r1 * gb;
;                     *(f32x4*)(xout + off + bj * 128) = v0; *(f32x4*)(xout + off + bj * 128 + 4) = v1; acc[ai][bj][m][0] = v0; acc[ai][bj][m][1] = v1; }
;                 asm volatile("" ::: "memory"); }
	v_pk_fma_f32 v[102:103], v[102:103], v[222:223], v[202:203]
	v_pk_fma_f32 v[104:105], v[104:105], v[224:225], v[204:205]
	v_pk_fma_f32 v[98:99], v[98:99], v[218:219], v[206:207]
	v_pk_fma_f32 v[100:101], v[100:101], v[220:221], v[208:209]
	v_pk_fma_f32 v[106:107], v[106:107], v[230:231], v[210:211]
	v_pk_fma_f32 v[108:109], v[108:109], v[232:233], v[212:213]
	v_pk_fma_f32 v[110:111], v[110:111], v[226:227], v[214:215]
	v_pk_fma_f32 v[112:113], v[112:113], v[228:229], v[216:217]
	global_store_dwordx4 v[162:163], v[98:101], off
	global_store_dwordx4 v[162:163], v[102:105], off offset:16
	global_store_dwordx4 v[162:163], v[110:113], off offset:512
	global_store_dwordx4 v[162:163], v[106:109], off offset:528
	v_add_u32_e32 v250, s54, v175
	v_ashrrev_i32_e32 v251, 31, v250
	v_lshlrev_b64 v[250:251], 10, v[250:251]
	v_lshl_add_u64 v[250:251], v[250:251], 0, v[142:143]
	v_lshlrev_b64 v[250:251], 2, v[250:251]
	v_lshl_add_u64 v[164:165], s[34:35], 0, v[250:251]
	v_lshl_add_u64 v[162:163], s[14:15], 0, v[250:251]
	ds_read_b32 v154, v185
	global_load_dwordx4 v[202:205], v[164:165], off offset:16
	global_load_dwordx4 v[206:209], v[164:165], off
	global_load_dwordx4 v[210:213], v[164:165], off offset:528
	global_load_dwordx4 v[214:217], v[164:165], off offset:512
	s_waitcnt lgkmcnt(1)
	v_pk_mul_f32 v[122:123], v[122:123], v[156:157] op_sel_hi:[1,0]
	v_pk_mul_f32 v[124:125], v[124:125], v[156:157] op_sel_hi:[1,0]
	v_pk_mul_f32 v[126:127], v[126:127], v[156:157] op_sel_hi:[1,0]
	v_pk_mul_f32 v[128:129], v[128:129], v[156:157] op_sel_hi:[1,0]
	v_pk_mul_f32 v[118:119], v[118:119], v[156:157] op_sel_hi:[1,0]
	v_pk_mul_f32 v[120:121], v[120:121], v[156:157] op_sel_hi:[1,0]
	v_pk_mul_f32 v[114:115], v[114:115], v[156:157] op_sel_hi:[1,0]
	v_pk_mul_f32 v[116:117], v[116:117], v[156:157] op_sel_hi:[1,0]
	s_waitcnt vmcnt(8)
	v_pk_fma_f32 v[126:127], v[126:127], v[222:223], v[234:235]
	v_pk_fma_f32 v[128:129], v[128:129], v[224:225], v[236:237]
	v_pk_fma_f32 v[122:123], v[122:123], v[218:219], v[238:239]
	v_pk_fma_f32 v[124:125], v[124:125], v[220:221], v[240:241]
	v_pk_fma_f32 v[114:115], v[114:115], v[230:231], v[146:147]
	v_pk_fma_f32 v[116:117], v[116:117], v[232:233], v[148:149]
	v_pk_fma_f32 v[118:119], v[118:119], v[226:227], v[150:151]
	v_pk_fma_f32 v[120:121], v[120:121], v[228:229], v[152:153]
	global_store_dwordx4 v[160:161], v[122:125], off
	global_store_dwordx4 v[160:161], v[126:129], off offset:16
	global_store_dwordx4 v[160:161], v[118:121], off offset:512
	global_store_dwordx4 v[160:161], v[114:117], off offset:528
	v_add_u32_e32 v250, s54, v176
	v_ashrrev_i32_e32 v251, 31, v250
	v_lshlrev_b64 v[250:251], 10, v[250:251]
	v_lshl_add_u64 v[250:251], v[250:251], 0, v[142:143]
	v_lshlrev_b64 v[250:251], 2, v[250:251]
	v_lshl_add_u64 v[158:159], s[34:35], 0, v[250:251]
	v_lshl_add_u64 v[160:161], s[14:15], 0, v[250:251]
	ds_read_b32 v156, v186
	global_load_dwordx4 v[234:237], v[158:159], off offset:16
	global_load_dwordx4 v[238:241], v[158:159], off
	global_load_dwordx4 v[146:149], v[158:159], off offset:528
	global_load_dwordx4 v[150:153], v[158:159], off offset:512
	s_waitcnt lgkmcnt(1)
	v_pk_mul_f32 v[94:95], v[94:95], v[154:155] op_sel_hi:[1,0]
	v_pk_mul_f32 v[96:97], v[96:97], v[154:155] op_sel_hi:[1,0]
	v_pk_mul_f32 v[90:91], v[90:91], v[154:155] op_sel_hi:[1,0]
	v_pk_mul_f32 v[92:93], v[92:93], v[154:155] op_sel_hi:[1,0]
	v_pk_mul_f32 v[78:79], v[78:79], v[154:155] op_sel_hi:[1,0]
	v_pk_mul_f32 v[80:81], v[80:81], v[154:155] op_sel_hi:[1,0]
	v_pk_mul_f32 v[74:75], v[74:75], v[154:155] op_sel_hi:[1,0]
	v_pk_mul_f32 v[76:77], v[76:77], v[154:155] op_sel_hi:[1,0]
	s_waitcnt vmcnt(8)
	v_pk_fma_f32 v[90:91], v[90:91], v[222:223], v[202:203]
	v_pk_fma_f32 v[92:93], v[92:93], v[224:225], v[204:205]
	v_pk_fma_f32 v[94:95], v[94:95], v[218:219], v[206:207]
	v_pk_fma_f32 v[96:97], v[96:97], v[220:221], v[208:209]
	v_pk_fma_f32 v[74:75], v[74:75], v[230:231], v[210:211]
	v_pk_fma_f32 v[76:77], v[76:77], v[232:233], v[212:213]
	v_pk_fma_f32 v[78:79], v[78:79], v[226:227], v[214:215]
	v_pk_fma_f32 v[80:81], v[80:81], v[228:229], v[216:217]
	global_store_dwordx4 v[162:163], v[94:97], off
	global_store_dwordx4 v[162:163], v[90:93], off offset:16
	global_store_dwordx4 v[162:163], v[78:81], off offset:512
	global_store_dwordx4 v[162:163], v[74:77], off offset:528
	v_add_u32_e32 v250, s54, v177
	v_ashrrev_i32_e32 v251, 31, v250
	v_lshlrev_b64 v[250:251], 10, v[250:251]
	v_lshl_add_u64 v[250:251], v[250:251], 0, v[142:143]
	v_lshlrev_b64 v[250:251], 2, v[250:251]
	v_lshl_add_u64 v[164:165], s[34:35], 0, v[250:251]
	v_lshl_add_u64 v[162:163], s[14:15], 0, v[250:251]
	ds_read_b32 v154, v187
	global_load_dwordx4 v[202:205], v[164:165], off offset:16
	global_load_dwordx4 v[206:209], v[164:165], off
	global_load_dwordx4 v[210:213], v[164:165], off offset:528
	global_load_dwordx4 v[214:217], v[164:165], off offset:512
	s_waitcnt lgkmcnt(1)
	v_pk_mul_f32 v[54:55], v[54:55], v[156:157] op_sel_hi:[1,0]
	v_pk_mul_f32 v[56:57], v[56:57], v[156:157] op_sel_hi:[1,0]
	v_pk_mul_f32 v[50:51], v[50:51], v[156:157] op_sel_hi:[1,0]
	v_pk_mul_f32 v[52:53], v[52:53], v[156:157] op_sel_hi:[1,0]
	v_pk_mul_f32 v[38:39], v[38:39], v[156:157] op_sel_hi:[1,0]
	v_pk_mul_f32 v[40:41], v[40:41], v[156:157] op_sel_hi:[1,0]
	v_pk_mul_f32 v[34:35], v[34:35], v[156:157] op_sel_hi:[1,0]
	v_pk_mul_f32 v[36:37], v[36:37], v[156:157] op_sel_hi:[1,0]
	s_waitcnt vmcnt(8)
; __device__ __forceinline__ float swap_add(float v) { auto rr = __builtin_amdgcn_permlane32_swap(__float_as_uint(v), __float_as_uint(v), false, false); return __uint_as_float(rr[0]) + __uint_as_float(rr[1]); }
;     __device__ __forceinline__ void exchange(const f32x4 (&acc)[2][2][4][2], const Unit& u, int e, int wr, int wc, int fr, int fq) const {
;     ...
; #pragma unroll
;         for (int ai = 0; ai < 2; ++ai)
; #pragma unroll
;             for (int m = 0; m < 4; ++m) { float q = 0.f;
; #pragma unroll
;                 for (int bj = 0; bj < 2; ++bj)
; #pragma unroll
;                     for (int n = 0; n < 2; ++n) { const f32x4 v = acc[ai][bj][m][n]; q += (v[0] * v[0] + v[1] * v[1]) + (v[2] * v[2] + v[3] * v[3]); }
;                 q += __int_as_float(__builtin_amdgcn_ds_bpermute((lid ^ 16) << 2, __float_as_int(q))); q = swap_add(q);
;                 if (fq == 0) P[(ai * 128 + wr * 64 + m * 16 + fr) * 4 + wc] = q; }
;     __device__ __forceinline__ void operator()(f32x4 (&acc)[2][2][4][2], const Unit& u, int wr, int wc, int fr, int fq) const {
;     ...
; #pragma unroll
;         for (int ai = 0; ai < 2; ++ai)
; #pragma unroll
;             for (int m = 0; m < 4; ++m) { const int rl = ai * 128 + wr * 64 + m * 16 + fr; const float r1 = S[rl]; const size_t off = (size_t)(u.pm * 256 + rl) * DM + col0;
; #pragma unroll
;                 for (int bj = 0; bj < 2; ++bj) { const f32x4 xa = *(const f32x4*)(xin + off + bj * 128), xb = *(const f32x4*)(xin + off + bj * 128 + 4);
;                     const f32x4 ga = *(const f32x4*)(gpost + col0 + bj * 128), gb = *(const f32x4*)(gpost + col0 + bj * 128 + 4);
;                     const f32x4 v0 = xa + acc[ai][bj][m][0] * r1 * ga, v1 = xb + acc[ai][bj][m][1] * r1 * gb;
;                     *(f32x4*)(xout + off + bj * 128) = v0; *(f32x4*)(xout + off + bj * 128 + 4) = v1; acc[ai][bj][m][0] = v0; acc[ai][bj][m][1] = v1; }
;                 asm volatile("" ::: "memory"); }
	v_pk_fma_f32 v[50:51], v[50:51], v[222:223], v[234:235]
	v_pk_fma_f32 v[52:53], v[52:53], v[224:225], v[236:237]
	v_pk_fma_f32 v[54:55], v[54:55], v[218:219], v[238:239]
	v_pk_fma_f32 v[56:57], v[56:57], v[220:221], v[240:241]
	v_pk_fma_f32 v[34:35], v[34:35], v[230:231], v[146:147]
	v_pk_fma_f32 v[36:37], v[36:37], v[232:233], v[148:149]
	v_pk_fma_f32 v[38:39], v[38:39], v[226:227], v[150:151]
	v_pk_fma_f32 v[40:41], v[40:41], v[228:229], v[152:153]
	global_store_dwordx4 v[160:161], v[54:57], off
	global_store_dwordx4 v[160:161], v[50:53], off offset:16
	global_store_dwordx4 v[160:161], v[38:41], off offset:512
	global_store_dwordx4 v[160:161], v[34:37], off offset:528
	v_add_u32_e32 v250, s54, v178
	v_ashrrev_i32_e32 v251, 31, v250
	v_lshlrev_b64 v[250:251], 10, v[250:251]
	v_lshl_add_u64 v[250:251], v[250:251], 0, v[142:143]
	v_lshlrev_b64 v[250:251], 2, v[250:251]
	v_lshl_add_u64 v[158:159], s[34:35], 0, v[250:251]
	v_lshl_add_u64 v[160:161], s[14:15], 0, v[250:251]
	ds_read_b32 v156, v188
	global_load_dwordx4 v[234:237], v[158:159], off offset:16
	global_load_dwordx4 v[238:241], v[158:159], off
	global_load_dwordx4 v[146:149], v[158:159], off offset:528
	global_load_dwordx4 v[150:153], v[158:159], off offset:512
	s_waitcnt lgkmcnt(1)
	v_pk_mul_f32 v[30:31], v[30:31], v[154:155] op_sel_hi:[1,0]
	v_pk_mul_f32 v[32:33], v[32:33], v[154:155] op_sel_hi:[1,0]
	v_pk_mul_f32 v[26:27], v[26:27], v[154:155] op_sel_hi:[1,0]
	v_pk_mul_f32 v[28:29], v[28:29], v[154:155] op_sel_hi:[1,0]
	v_pk_mul_f32 v[22:23], v[22:23], v[154:155] op_sel_hi:[1,0]
	v_pk_mul_f32 v[24:25], v[24:25], v[154:155] op_sel_hi:[1,0]
	v_pk_mul_f32 v[18:19], v[18:19], v[154:155] op_sel_hi:[1,0]
	v_pk_mul_f32 v[20:21], v[20:21], v[154:155] op_sel_hi:[1,0]
	s_waitcnt vmcnt(8)
	v_pk_fma_f32 v[26:27], v[26:27], v[222:223], v[202:203]
	v_pk_fma_f32 v[28:29], v[28:29], v[224:225], v[204:205]
	v_pk_fma_f32 v[30:31], v[30:31], v[218:219], v[206:207]
	v_pk_fma_f32 v[32:33], v[32:33], v[220:221], v[208:209]
	v_pk_fma_f32 v[18:19], v[18:19], v[230:231], v[210:211]
	v_pk_fma_f32 v[20:21], v[20:21], v[232:233], v[212:213]
	v_pk_fma_f32 v[22:23], v[22:23], v[226:227], v[214:215]
	v_pk_fma_f32 v[24:25], v[24:25], v[228:229], v[216:217]
	global_store_dwordx4 v[162:163], v[30:33], off
	global_store_dwordx4 v[162:163], v[26:29], off offset:16
	global_store_dwordx4 v[162:163], v[22:25], off offset:512
	global_store_dwordx4 v[162:163], v[18:21], off offset:528
	s_waitcnt lgkmcnt(0)
	v_pk_mul_f32 v[14:15], v[14:15], v[156:157] op_sel_hi:[1,0]
	v_pk_mul_f32 v[16:17], v[16:17], v[156:157] op_sel_hi:[1,0]
	v_pk_mul_f32 v[10:11], v[10:11], v[156:157] op_sel_hi:[1,0]
	v_pk_mul_f32 v[12:13], v[12:13], v[156:157] op_sel_hi:[1,0]
	v_pk_mul_f32 v[6:7], v[6:7], v[156:157] op_sel_hi:[1,0]
	v_pk_mul_f32 v[8:9], v[8:9], v[156:157] op_sel_hi:[1,0]
	v_pk_mul_f32 v[2:3], v[2:3], v[156:157] op_sel_hi:[1,0]
	v_pk_mul_f32 v[4:5], v[4:5], v[156:157] op_sel_hi:[1,0]
	s_waitcnt vmcnt(4)
	v_pk_fma_f32 v[10:11], v[10:11], v[222:223], v[234:235]
	v_pk_fma_f32 v[12:13], v[12:13], v[224:225], v[236:237]
	v_pk_fma_f32 v[14:15], v[14:15], v[218:219], v[238:239]
	v_pk_fma_f32 v[16:17], v[16:17], v[220:221], v[240:241]
	v_pk_fma_f32 v[2:3], v[2:3], v[230:231], v[146:147]
	v_pk_fma_f32 v[4:5], v[4:5], v[232:233], v[148:149]
	v_pk_fma_f32 v[6:7], v[6:7], v[226:227], v[150:151]
	v_pk_fma_f32 v[8:9], v[8:9], v[228:229], v[152:153]
	global_store_dwordx4 v[160:161], v[14:17], off
	global_store_dwordx4 v[160:161], v[10:13], off offset:16
	global_store_dwordx4 v[160:161], v[6:9], off offset:512
	global_store_dwordx4 v[160:161], v[2:5], off offset:528
	v_add_u32_e32 v146, s54, v172
	v_ashrrev_i32_e32 v147, 31, v146
	v_add_u32_e32 v148, s54, v173
	v_ashrrev_i32_e32 v149, 31, v148
	v_add_u32_e32 v150, s54, v174
	v_ashrrev_i32_e32 v151, 31, v150
	v_add_u32_e32 v152, s54, v175
	v_ashrrev_i32_e32 v153, 31, v152
	v_add_u32_e32 v156, s54, v176
	v_ashrrev_i32_e32 v157, 31, v156
	v_add_u32_e32 v158, s54, v177
	v_ashrrev_i32_e32 v159, 31, v158
	v_add_u32_e32 v166, s54, v178
	v_ashrrev_i32_e32 v167, 31, v166
	s_cbranch_vccnz .LBB0_272
	v_mul_f32_e32 v154, v43, v43
	v_mul_f32_e32 v155, v45, v45
	v_fmac_f32_e32 v154, v42, v42
	v_fmac_f32_e32 v155, v44, v44
	v_add_f32_e32 v154, v154, v155
	v_mul_f32_e32 v155, v47, v47
	v_mul_f32_e32 v160, v49, v49
	v_fmac_f32_e32 v155, v46, v46
	v_fmac_f32_e32 v160, v48, v48
	v_add_f32_e32 v155, v155, v160
	v_add_f32_e32 v154, v154, v155
	v_mul_f32_e32 v155, v63, v63
	v_mul_f32_e32 v160, v65, v65
	v_fmac_f32_e32 v155, v62, v62
	v_fmac_f32_e32 v160, v64, v64
	v_add_f32_e32 v155, v155, v160
	v_add_f32_e32 v154, v154, v155
	v_mul_f32_e32 v155, v59, v59
	v_mul_f32_e32 v160, v61, v61
	v_fmac_f32_e32 v155, v58, v58
	v_fmac_f32_e32 v160, v60, v60
	v_add_f32_e32 v155, v155, v160
	v_add_f32_e32 v154, v154, v155
	ds_bpermute_b32 v155, v171, v154
	s_waitcnt lgkmcnt(0)
	v_add_f32_e32 v154, v154, v155
	v_mov_b32_e32 v155, v154
	s_nop 1
	v_permlane32_swap_b32_e32 v154, v155
	s_and_saveexec_b64 s[54:55], s[42:43]
	v_add_f32_e32 v154, v154, v155
	ds_write_b32 v191, v154
	s_or_b64 exec, exec, s[54:55]
	v_mul_f32_e32 v154, v67, v67
	v_mul_f32_e32 v155, v69, v69
	v_fmac_f32_e32 v154, v66, v66
	v_fmac_f32_e32 v155, v68, v68
	v_add_f32_e32 v154, v154, v155
	v_mul_f32_e32 v155, v71, v71
	v_mul_f32_e32 v160, v73, v73
	v_fmac_f32_e32 v155, v70, v70
	v_fmac_f32_e32 v160, v72, v72
	v_add_f32_e32 v155, v155, v160
	v_add_f32_e32 v154, v154, v155
	v_mul_f32_e32 v155, v87, v87
	v_mul_f32_e32 v160, v89, v89
	v_fmac_f32_e32 v155, v86, v86
	v_fmac_f32_e32 v160, v88, v88
	v_add_f32_e32 v155, v155, v160
	v_add_f32_e32 v154, v154, v155
	v_mul_f32_e32 v155, v83, v83
	v_mul_f32_e32 v160, v85, v85
	v_fmac_f32_e32 v155, v82, v82
	v_fmac_f32_e32 v160, v84, v84
	v_add_f32_e32 v155, v155, v160
	v_add_f32_e32 v154, v154, v155
	ds_bpermute_b32 v155, v171, v154
	s_waitcnt lgkmcnt(0)
; __device__ __forceinline__ float swap_add(float v) { auto rr = __builtin_amdgcn_permlane32_swap(__float_as_uint(v), __float_as_uint(v), false, false); return __uint_as_float(rr[0]) + __uint_as_float(rr[1]); }
;     __device__ __forceinline__ void exchange(const f32x4 (&acc)[2][2][4][2], const Unit& u, int e, int wr, int wc, int fr, int fq) const {
;     ...
; #pragma unroll
;         for (int ai = 0; ai < 2; ++ai)
; #pragma unroll
;             for (int m = 0; m < 4; ++m) { float q = 0.f;
; #pragma unroll
;                 for (int bj = 0; bj < 2; ++bj)
; #pragma unroll
;                     for (int n = 0; n < 2; ++n) { const f32x4 v = acc[ai][bj][m][n]; q += (v[0] * v[0] + v[1] * v[1]) + (v[2] * v[2] + v[3] * v[3]); }
;                 q += __int_as_float(__builtin_amdgcn_ds_bpermute((lid ^ 16) << 2, __float_as_int(q))); q = swap_add(q);
;                 if (fq == 0) P[(ai * 128 + wr * 64 + m * 16 + fr) * 4 + wc] = q; }
;         __syncthreads();
;         float* xb = xbuf + (size_t)e * T * 4 + (size_t)u.pm * 256 * 4; unsigned* c = cnt + (e * 64 + u.pm) * 64;
;         if (tid < 256) { const float tot = (P[tid * 4] + P[tid * 4 + 1]) + (P[tid * 4 + 2] + P[tid * 4 + 3]);
;             __hip_atomic_store(xb + tid * 4 + u.pn, tot, __ATOMIC_RELAXED, __HIP_MEMORY_SCOPE_AGENT); }
	v_add_f32_e32 v154, v154, v155
	v_mov_b32_e32 v155, v154
	s_nop 1
	v_permlane32_swap_b32_e32 v154, v155
	s_and_saveexec_b64 s[54:55], s[42:43]
	v_add_f32_e32 v154, v154, v155
	ds_write_b32 v191, v154 offset:256
	s_or_b64 exec, exec, s[54:55]
	v_mul_f32_e32 v154, v99, v99
	v_mul_f32_e32 v155, v101, v101
	v_fmac_f32_e32 v154, v98, v98
	v_fmac_f32_e32 v155, v100, v100
	v_add_f32_e32 v154, v154, v155
	v_mul_f32_e32 v155, v103, v103
	v_mul_f32_e32 v160, v105, v105
	v_fmac_f32_e32 v155, v102, v102
	v_fmac_f32_e32 v160, v104, v104
	v_add_f32_e32 v155, v155, v160
	v_add_f32_e32 v154, v154, v155
	v_mul_f32_e32 v155, v111, v111
	v_mul_f32_e32 v160, v113, v113
	v_fmac_f32_e32 v155, v110, v110
	v_fmac_f32_e32 v160, v112, v112
	v_add_f32_e32 v155, v155, v160
	v_add_f32_e32 v154, v154, v155
	v_mul_f32_e32 v155, v107, v107
	v_mul_f32_e32 v160, v109, v109
	v_fmac_f32_e32 v155, v106, v106
	v_fmac_f32_e32 v160, v108, v108
	v_add_f32_e32 v155, v155, v160
	v_add_f32_e32 v154, v154, v155
	ds_bpermute_b32 v155, v171, v154
	s_waitcnt lgkmcnt(0)
	v_add_f32_e32 v154, v154, v155
	v_mov_b32_e32 v155, v154
	s_nop 1
	v_permlane32_swap_b32_e32 v154, v155
	s_and_saveexec_b64 s[54:55], s[42:43]
	v_add_f32_e32 v154, v154, v155
	ds_write_b32 v191, v154 offset:512
	s_or_b64 exec, exec, s[54:55]
	v_mul_f32_e32 v154, v123, v123
	v_mul_f32_e32 v155, v125, v125
	v_fmac_f32_e32 v154, v122, v122
	v_fmac_f32_e32 v155, v124, v124
	v_add_f32_e32 v154, v154, v155
	v_mul_f32_e32 v155, v127, v127
	v_mul_f32_e32 v160, v129, v129
	v_fmac_f32_e32 v155, v126, v126
	v_fmac_f32_e32 v160, v128, v128
	v_add_f32_e32 v155, v155, v160
	v_add_f32_e32 v154, v154, v155
	v_mul_f32_e32 v155, v119, v119
	v_mul_f32_e32 v160, v121, v121
	v_fmac_f32_e32 v155, v118, v118
	v_fmac_f32_e32 v160, v120, v120
	v_add_f32_e32 v155, v155, v160
	v_add_f32_e32 v154, v154, v155
	v_mul_f32_e32 v155, v115, v115
	v_mul_f32_e32 v160, v117, v117
	v_fmac_f32_e32 v155, v114, v114
	v_fmac_f32_e32 v160, v116, v116
	v_add_f32_e32 v155, v155, v160
	v_add_f32_e32 v154, v154, v155
	ds_bpermute_b32 v155, v171, v154
	s_waitcnt lgkmcnt(0)
	v_add_f32_e32 v154, v154, v155
	v_mov_b32_e32 v155, v154
	s_nop 1
	v_permlane32_swap_b32_e32 v154, v155
	s_and_saveexec_b64 s[54:55], s[42:43]
	v_add_f32_e32 v154, v154, v155
	ds_write_b32 v191, v154 offset:768
	s_or_b64 exec, exec, s[54:55]
	v_mul_f32_e32 v154, v95, v95
	v_mul_f32_e32 v155, v97, v97
	v_fmac_f32_e32 v154, v94, v94
	v_fmac_f32_e32 v155, v96, v96
	v_add_f32_e32 v154, v154, v155
	v_mul_f32_e32 v155, v91, v91
	v_mul_f32_e32 v160, v93, v93
	v_fmac_f32_e32 v155, v90, v90
	v_fmac_f32_e32 v160, v92, v92
	v_add_f32_e32 v155, v155, v160
	v_add_f32_e32 v154, v154, v155
	v_mul_f32_e32 v155, v79, v79
	v_mul_f32_e32 v160, v81, v81
	v_fmac_f32_e32 v155, v78, v78
	v_fmac_f32_e32 v160, v80, v80
	v_add_f32_e32 v155, v155, v160
	v_add_f32_e32 v154, v154, v155
	v_mul_f32_e32 v155, v75, v75
	v_mul_f32_e32 v160, v77, v77
	v_fmac_f32_e32 v155, v74, v74
	v_fmac_f32_e32 v160, v76, v76
	v_add_f32_e32 v155, v155, v160
	v_add_f32_e32 v154, v154, v155
	ds_bpermute_b32 v155, v171, v154
	s_waitcnt lgkmcnt(0)
	v_add_f32_e32 v154, v154, v155
	v_mov_b32_e32 v155, v154
	s_nop 1
	v_permlane32_swap_b32_e32 v154, v155
	s_and_saveexec_b64 s[54:55], s[42:43]
	v_add_f32_e32 v154, v154, v155
	ds_write_b32 v191, v154 offset:2048
	s_or_b64 exec, exec, s[54:55]
	v_mul_f32_e32 v154, v55, v55
	v_mul_f32_e32 v155, v57, v57
	v_fmac_f32_e32 v154, v54, v54
	v_fmac_f32_e32 v155, v56, v56
	v_add_f32_e32 v154, v154, v155
	v_mul_f32_e32 v155, v51, v51
	v_mul_f32_e32 v160, v53, v53
	v_fmac_f32_e32 v155, v50, v50
	v_fmac_f32_e32 v160, v52, v52
	v_add_f32_e32 v155, v155, v160
	v_add_f32_e32 v154, v154, v155
	v_mul_f32_e32 v155, v39, v39
	v_mul_f32_e32 v160, v41, v41
	v_fmac_f32_e32 v155, v38, v38
	v_fmac_f32_e32 v160, v40, v40
	v_add_f32_e32 v155, v155, v160
	v_add_f32_e32 v154, v154, v155
	v_mul_f32_e32 v155, v35, v35
	v_mul_f32_e32 v160, v37, v37
	v_fmac_f32_e32 v155, v34, v34
	v_fmac_f32_e32 v160, v36, v36
	v_add_f32_e32 v155, v155, v160
	v_add_f32_e32 v154, v154, v155
	ds_bpermute_b32 v155, v171, v154
	s_waitcnt lgkmcnt(0)
	v_add_f32_e32 v154, v154, v155
	v_mov_b32_e32 v155, v154
	s_nop 1
	v_permlane32_swap_b32_e32 v154, v155
	s_and_saveexec_b64 s[54:55], s[42:43]
	v_add_f32_e32 v154, v154, v155
	ds_write_b32 v191, v154 offset:2304
	s_or_b64 exec, exec, s[54:55]
	v_mul_f32_e32 v154, v31, v31
	v_mul_f32_e32 v155, v33, v33
	v_fmac_f32_e32 v154, v30, v30
	v_fmac_f32_e32 v155, v32, v32
	v_add_f32_e32 v154, v154, v155
	v_mul_f32_e32 v155, v27, v27
	v_mul_f32_e32 v160, v29, v29
	v_fmac_f32_e32 v155, v26, v26
	v_fmac_f32_e32 v160, v28, v28
	v_add_f32_e32 v155, v155, v160
	v_add_f32_e32 v154, v154, v155
	v_mul_f32_e32 v155, v23, v23
	v_mul_f32_e32 v160, v25, v25
	v_fmac_f32_e32 v155, v22, v22
	v_fmac_f32_e32 v160, v24, v24
	v_add_f32_e32 v155, v155, v160
	v_add_f32_e32 v154, v154, v155
	v_mul_f32_e32 v155, v19, v19
	v_mul_f32_e32 v160, v21, v21
	v_fmac_f32_e32 v155, v18, v18
	v_fmac_f32_e32 v160, v20, v20
	v_add_f32_e32 v155, v155, v160
	v_add_f32_e32 v154, v154, v155
	ds_bpermute_b32 v155, v171, v154
	s_waitcnt lgkmcnt(0)
	v_add_f32_e32 v154, v154, v155
	v_mov_b32_e32 v155, v154
	s_nop 1
	v_permlane32_swap_b32_e32 v154, v155
	s_and_saveexec_b64 s[54:55], s[42:43]
	v_add_f32_e32 v154, v154, v155
	ds_write_b32 v191, v154 offset:2560
	s_or_b64 exec, exec, s[54:55]
	v_mul_f32_e32 v154, v15, v15
	v_mul_f32_e32 v155, v17, v17
	v_fmac_f32_e32 v154, v14, v14
	v_fmac_f32_e32 v155, v16, v16
	v_add_f32_e32 v154, v154, v155
	v_mul_f32_e32 v155, v11, v11
	v_mul_f32_e32 v160, v13, v13
	v_fmac_f32_e32 v155, v10, v10
	v_fmac_f32_e32 v160, v12, v12
	v_add_f32_e32 v155, v155, v160
	v_add_f32_e32 v154, v154, v155
	v_mul_f32_e32 v155, v7, v7
	v_mul_f32_e32 v160, v9, v9
	v_fmac_f32_e32 v155, v6, v6
	v_fmac_f32_e32 v160, v8, v8
	v_add_f32_e32 v155, v155, v160
	v_add_f32_e32 v154, v154, v155
	v_mul_f32_e32 v155, v3, v3
	v_mul_f32_e32 v160, v5, v5
	v_fmac_f32_e32 v155, v2, v2
	v_fmac_f32_e32 v160, v4, v4
	v_add_f32_e32 v155, v155, v160
	v_add_f32_e32 v154, v154, v155
	ds_bpermute_b32 v155, v171, v154
	s_waitcnt lgkmcnt(0)
	v_add_f32_e32 v154, v154, v155
	v_mov_b32_e32 v155, v154
	s_nop 1
	v_permlane32_swap_b32_e32 v154, v155
	s_and_saveexec_b64 s[54:55], s[42:43]
	v_add_f32_e32 v154, v154, v155
	ds_write_b32 v191, v154 offset:2816
	s_or_b64 exec, exec, s[54:55]
	s_add_u32 s12, s97, s12
	s_addc_u32 s13, s72, s13
	v_lshl_add_u64 v[154:155], v[136:137], 2, s[12:13]
	s_waitcnt lgkmcnt(0)
	s_barrier
	s_and_saveexec_b64 s[12:13], s[44:45]
	s_cbranch_execz .LBB0_254
	ds_read_b128 v[202:205], v179
	s_ashr_i32 s77, s76, 31
	v_lshl_add_u64 v[162:163], s[76:77], 2, v[154:155]
	s_waitcnt lgkmcnt(0)
	v_mov_b32_e32 v160, v203
	v_mov_b32_e32 v161, v204
	v_mov_b32_e32 v203, v205
	v_pk_add_f32 v[160:161], v[160:161], v[202:203]
	s_nop 0
	v_pk_add_f32 v[160:161], v[160:161], v[160:161] op_sel:[0,1] op_sel_hi:[1,0]
	global_store_dword v[162:163], v160, off sc1

; __global__ void __launch_bounds__(NTHREADS, 2) fwd_megakernel(Args a_unused) {
;     ...
;     for (int ph = lo; ph < hi; ++ph) {
;         CArgs ap = ap0; asm volatile("" : "+s"(ap));
;     ...
;         if (ph + 1 < hi) { if (hi > 4096) cg::this_grid().sync();
;             xcd_barrier(gbar, t0); if constexpr (PROBE_SYNC != 0) xcd_barrier(gbar, t0); }
.LBB0_886:
	s_add_i32 s72, s72, 1
	v_readlane_b32 s18, v254, 51
	v_readlane_b32 s20, v254, 53
	v_readlane_b32 s38, v254, 55
	v_readlane_b32 s12, v254, 57
	s_min_i32 s0, s73, 14
	s_cmp_ge_i32 s72, s0
	s_mov_b64 s[0:1], -1
	v_readlane_b32 s19, v254, 52
	v_readlane_b32 s21, v254, 54
	v_readlane_b32 s39, v254, 56
	v_readlane_b32 s13, v254, 58
	s_cbranch_scc0 .LBB0_887
	s_getpc_b64 s[98:99]
